# gqa loop VALU trims: cross-half row-max exchange only on the rescale path, K/V tile loads through SGPR base + 32-bit offsets (no 64-bit address VALU per tile)
# baseline (speedup 1.0000x reference)
.LBB0_1153:
	v_add_u32_e32 v221, v142, v144
	v_lshlrev_b32_e32 v221, 1, v221
	s_mul_i32 s70, s84, 0x9000
	v_add_u32_e32 v208, s70, v154
	s_mov_b32 s71, s65
	s_mul_i32 s68, s71, 0x9000
	s_mov_b32 s65, s84
	v_add_u32_e32 v209, s68, v155
	v_add_u32_e32 v210, 0x4000, v209
	v_add_u32_e32 v211, 0x5000, v209
	ds_read_b128 v[156:159], v208
	ds_read_b128 v[160:163], v208 offset:4608
	ds_read_b128 v[164:167], v208 offset:32
	ds_read_b128 v[168:171], v208 offset:4640
	ds_read_b128 v[172:175], v208 offset:64
	ds_read_b128 v[176:179], v208 offset:4672
	ds_read_b128 v[184:187], v208 offset:96
	ds_read_b128 v[188:191], v208 offset:4704
	s_waitcnt lgkmcnt(6)
	v_mfma_f32_32x32x16_bf16 v[64:79], v[156:159], v[108:111], v[32:47]
	ds_read_b64 v[156:157], v210 offset:1024
	ds_read_b64 v[158:159], v210 offset:1040
	s_mul_i32 s72, s66, 0x9000
	s_add_i32 s73, s72, 0
	v_add3_u32 v218, s73, v150, v151
	v_add3_u32 v219, s73, v152, v153
	v_mfma_f32_32x32x16_bf16 v[80:95], v[160:163], v[108:111], v[32:47]
	ds_read_b64 v[160:161], v211 offset:1536
	ds_read_b64 v[162:163], v211 offset:1552
	s_waitcnt vmcnt(0)
	ds_write_b128 v218, v[116:119]
	ds_write_b128 v219, v[124:127] offset:17408
	s_add_i32 s68, s25, -2
	s_cmp_gt_u32 s68, 33
	s_cbranch_scc1 .Lg4e_nogl
	s_cmp_lt_u32 s68, 30
	s_cselect_b64 s[74:75], -1, 0
	s_and_b64 s[76:77], s[74:75], exec
	s_cselect_b32 s68, 0, 0xffffffe0
	s_add_i32 s68, s68, s25
	s_and_b64 s[76:77], s[74:75], exec
	s_cselect_b32 s73, s21, s27
	s_cselect_b32 s78, s20, s26
	s_lshl_b64 s[76:77], s[68:69], 14
	s_add_u32 s76, s78, s76
	s_addc_u32 s77, s73, s77
	s_and_b64 s[78:79], s[74:75], exec
	s_cselect_b32 s73, s23, s64
	s_cselect_b32 s80, s22, s63
	s_lshl_b32 s68, s68, 6
	s_lshl_b64 s[78:79], s[68:69], 1
	s_add_u32 s78, s80, s78
	s_addc_u32 s79, s73, s79
	s_and_b64 s[74:75], s[74:75], exec
	s_cselect_b32 s68, 12, 9
	global_load_dwordx4 v[116:119], v221, s[76:77]
	v_lshl_add_u32 v222, v146, s68, v128
	global_load_dwordx4 v[124:127], v222, s[78:79]
.Lg4e_nogl:
	s_waitcnt lgkmcnt(10)
	v_mfma_f32_32x32x16_bf16 v[64:79], v[164:167], v[104:107], v[64:79]
	ds_read_b64 v[164:165], v210 offset:1056
	ds_read_b64 v[166:167], v210 offset:1072
	v_mfma_f32_32x32x16_bf16 v[80:95], v[168:171], v[104:107], v[80:95]
	ds_read_b64 v[168:169], v211 offset:1568
	ds_read_b64 v[170:171], v211 offset:1584
	s_waitcnt lgkmcnt(12)
	v_mfma_f32_32x32x16_bf16 v[64:79], v[172:175], v[100:103], v[64:79]
	ds_read_b64 v[172:173], v210 offset:1088
	ds_read_b64 v[174:175], v210 offset:1104
	v_mfma_f32_32x32x16_bf16 v[80:95], v[176:179], v[100:103], v[80:95]
	ds_read_b64 v[176:177], v211 offset:1600
	ds_read_b64 v[178:179], v211 offset:1616
	s_waitcnt lgkmcnt(14)
	v_mfma_f32_32x32x16_bf16 v[64:79], v[184:187], v[96:99], v[64:79]
	ds_read_b64 v[184:185], v210 offset:1120
	ds_read_b64 v[186:187], v210 offset:1136
	v_mfma_f32_32x32x16_bf16 v[80:95], v[188:191], v[96:99], v[80:95]
	ds_read_b64 v[188:189], v211 offset:1632
	ds_read_b64 v[190:191], v211 offset:1648
	s_waitcnt lgkmcnt(14)
	v_mfma_f32_32x32x16_bf16 v[16:31], v[156:159], v[134:137], v[16:31]
	v_mfma_f32_32x32x16_bf16 v[0:15], v[160:163], v[134:137], v[0:15]
	s_waitcnt lgkmcnt(8)
	v_mfma_f32_32x32x16_bf16 v[16:31], v[164:167], v[130:133], v[16:31]
	v_mfma_f32_32x32x16_bf16 v[0:15], v[168:171], v[130:133], v[0:15]
	s_waitcnt lgkmcnt(4)
	v_mfma_f32_32x32x16_bf16 v[16:31], v[172:175], v[120:123], v[16:31]
	v_mfma_f32_32x32x16_bf16 v[0:15], v[176:179], v[120:123], v[0:15]
	s_waitcnt lgkmcnt(0)
	v_mfma_f32_32x32x16_bf16 v[16:31], v[184:187], v[112:115], v[16:31]
	v_mfma_f32_32x32x16_bf16 v[0:15], v[188:191], v[112:115], v[0:15]
	v_max3_f32 v212, v64, v80, v68
	v_max3_f32 v213, v65, v81, v69
	v_max3_f32 v214, v66, v82, v70
	v_max3_f32 v215, v67, v83, v71
	v_max3_f32 v212, v212, v84, v72
	v_max3_f32 v213, v213, v85, v73
	v_max3_f32 v214, v214, v86, v74
	v_max3_f32 v215, v215, v87, v75
	v_max3_f32 v212, v212, v88, v76
	v_max3_f32 v213, v213, v89, v77
	v_max3_f32 v214, v214, v90, v78
	v_max3_f32 v215, v215, v91, v79
	v_max_f32_e32 v212, v212, v92
	v_max_f32_e32 v213, v213, v93
	v_max_f32_e32 v214, v214, v94
	v_max_f32_e32 v215, v215, v95
	v_max3_f32 v212, v212, v213, v214
	v_max_f32_e32 v212, v212, v215
	v_cmp_lt_f32_e32 vcc, 0x41000000, v212
	s_cbranch_vccz .Lg4e_join
	v_mov_b32_e32 v216, v212
	v_mov_b32_e32 v217, v212
	s_nop 1
	v_permlane32_swap_b32_e32 v216, v217
	v_max_f32_e32 v212, v216, v217
	v_max_f32_e32 v222, 0, v212
	v_add_f32_e32 v149, v149, v222
	v_exp_f32_e64 v216, -v222
	v_xor_b32_e32 v32, 0x80000000, v149
	v_pk_add_f32 v[64:65], v[64:65], v[222:223] op_sel_hi:[1,0] neg_lo:[0,1] neg_hi:[0,1]
	v_pk_add_f32 v[66:67], v[66:67], v[222:223] op_sel_hi:[1,0] neg_lo:[0,1] neg_hi:[0,1]
	v_pk_add_f32 v[68:69], v[68:69], v[222:223] op_sel_hi:[1,0] neg_lo:[0,1] neg_hi:[0,1]
	v_pk_add_f32 v[70:71], v[70:71], v[222:223] op_sel_hi:[1,0] neg_lo:[0,1] neg_hi:[0,1]
	v_pk_add_f32 v[72:73], v[72:73], v[222:223] op_sel_hi:[1,0] neg_lo:[0,1] neg_hi:[0,1]
	v_pk_add_f32 v[74:75], v[74:75], v[222:223] op_sel_hi:[1,0] neg_lo:[0,1] neg_hi:[0,1]
	v_pk_add_f32 v[76:77], v[76:77], v[222:223] op_sel_hi:[1,0] neg_lo:[0,1] neg_hi:[0,1]
	v_pk_add_f32 v[78:79], v[78:79], v[222:223] op_sel_hi:[1,0] neg_lo:[0,1] neg_hi:[0,1]
	v_pk_add_f32 v[80:81], v[80:81], v[222:223] op_sel_hi:[1,0] neg_lo:[0,1] neg_hi:[0,1]
	v_pk_add_f32 v[82:83], v[82:83], v[222:223] op_sel_hi:[1,0] neg_lo:[0,1] neg_hi:[0,1]
	v_pk_add_f32 v[84:85], v[84:85], v[222:223] op_sel_hi:[1,0] neg_lo:[0,1] neg_hi:[0,1]
	v_pk_add_f32 v[86:87], v[86:87], v[222:223] op_sel_hi:[1,0] neg_lo:[0,1] neg_hi:[0,1]
	v_pk_add_f32 v[88:89], v[88:89], v[222:223] op_sel_hi:[1,0] neg_lo:[0,1] neg_hi:[0,1]
	v_pk_add_f32 v[90:91], v[90:91], v[222:223] op_sel_hi:[1,0] neg_lo:[0,1] neg_hi:[0,1]
	v_pk_add_f32 v[92:93], v[92:93], v[222:223] op_sel_hi:[1,0] neg_lo:[0,1] neg_hi:[0,1]
	v_pk_add_f32 v[94:95], v[94:95], v[222:223] op_sel_hi:[1,0] neg_lo:[0,1] neg_hi:[0,1]
	v_mov_b32_e32 v33, v32
	v_mov_b32_e32 v34, v32
	v_mov_b32_e32 v35, v32
	v_mov_b32_e32 v36, v32
	v_mov_b32_e32 v37, v32
	v_mov_b32_e32 v38, v32
	v_mov_b32_e32 v39, v32
	v_mov_b32_e32 v40, v32
	v_mov_b32_e32 v41, v32
	v_mov_b32_e32 v42, v32
	v_mov_b32_e32 v43, v32
	v_mov_b32_e32 v44, v32
	v_mov_b32_e32 v45, v32
	v_mov_b32_e32 v46, v32
	v_mov_b32_e32 v47, v32
	v_mul_f32_e32 v148, v148, v216
	v_pk_mul_f32 v[16:17], v[16:17], v[216:217] op_sel_hi:[1,0]
	v_pk_mul_f32 v[18:19], v[18:19], v[216:217] op_sel_hi:[1,0]
	v_pk_mul_f32 v[20:21], v[20:21], v[216:217] op_sel_hi:[1,0]
	v_pk_mul_f32 v[22:23], v[22:23], v[216:217] op_sel_hi:[1,0]
	v_pk_mul_f32 v[24:25], v[24:25], v[216:217] op_sel_hi:[1,0]
	v_pk_mul_f32 v[26:27], v[26:27], v[216:217] op_sel_hi:[1,0]
	v_pk_mul_f32 v[28:29], v[28:29], v[216:217] op_sel_hi:[1,0]
	v_pk_mul_f32 v[30:31], v[30:31], v[216:217] op_sel_hi:[1,0]
	v_pk_mul_f32 v[0:1], v[0:1], v[216:217] op_sel_hi:[1,0]
	v_pk_mul_f32 v[2:3], v[2:3], v[216:217] op_sel_hi:[1,0]
	v_pk_mul_f32 v[4:5], v[4:5], v[216:217] op_sel_hi:[1,0]
	v_pk_mul_f32 v[6:7], v[6:7], v[216:217] op_sel_hi:[1,0]
	v_pk_mul_f32 v[8:9], v[8:9], v[216:217] op_sel_hi:[1,0]
	v_pk_mul_f32 v[10:11], v[10:11], v[216:217] op_sel_hi:[1,0]
	v_pk_mul_f32 v[12:13], v[12:13], v[216:217] op_sel_hi:[1,0]
	v_pk_mul_f32 v[14:15], v[14:15], v[216:217] op_sel_hi:[1,0]

.Lg4_loop:
	s_mul_i32 s70, s84, 0x9000
	v_add_u32_e32 v208, s70, v154
	s_mov_b32 s71, s65
	s_mul_i32 s68, s71, 0x9000
	s_mov_b32 s65, s84
	v_add_u32_e32 v209, s68, v155
	v_add_u32_e32 v210, 0x4000, v209
	v_add_u32_e32 v211, 0x5000, v209
	ds_read_b128 v[156:159], v208
	ds_read_b128 v[160:163], v208 offset:4608
	ds_read_b128 v[164:167], v208 offset:32
	ds_read_b128 v[168:171], v208 offset:4640
	ds_read_b128 v[172:175], v208 offset:64
	ds_read_b128 v[176:179], v208 offset:4672
	ds_read_b128 v[184:187], v208 offset:96
	ds_read_b128 v[188:191], v208 offset:4704
	s_mul_i32 s72, s66, 0x9000
	s_add_i32 s73, s72, 0
	v_add3_u32 v218, s73, v150, v151
	v_add3_u32 v219, s73, v152, v153
	v_exp_f32_e32 v64, v64
	v_exp_f32_e32 v80, v80
	v_exp_f32_e32 v65, v65
	v_exp_f32_e32 v81, v81
	v_exp_f32_e32 v66, v66
	s_waitcnt lgkmcnt(6)
	v_mfma_f32_32x32x16_bf16 v[48:63], v[156:159], v[108:111], v[32:47]
	ds_read_b64 v[156:157], v210 offset:1024
	ds_read_b64 v[158:159], v210 offset:1040
	v_pk_add_f32 v[214:215], v[64:65], v[80:81]
	v_exp_f32_e32 v82, v82
	v_exp_f32_e32 v67, v67
	v_exp_f32_e32 v83, v83
	v_mfma_f32_32x32x16_bf16 v[192:207], v[160:163], v[108:111], v[32:47]
	ds_read_b64 v[160:161], v211 offset:1536
	ds_read_b64 v[162:163], v211 offset:1552
	s_waitcnt vmcnt(0)
	ds_write_b128 v218, v[116:119]
	ds_write_b128 v219, v[124:127] offset:17408
	s_add_i32 s68, s25, -2
	s_cmp_gt_u32 s68, 33
	s_cbranch_scc1 .Lg4b_nogl
	s_cmp_lt_u32 s68, 30
	s_cselect_b64 s[74:75], -1, 0
	s_and_b64 s[76:77], s[74:75], exec
	s_cselect_b32 s68, 0, 0xffffffe0
	s_add_i32 s68, s68, s25
	s_and_b64 s[76:77], s[74:75], exec
	s_cselect_b32 s73, s21, s27
	s_cselect_b32 s78, s20, s26
	s_lshl_b64 s[76:77], s[68:69], 14
	s_add_u32 s76, s78, s76
	s_addc_u32 s77, s73, s77
	s_and_b64 s[78:79], s[74:75], exec
	s_cselect_b32 s73, s23, s64
	s_cselect_b32 s80, s22, s63
	s_lshl_b32 s68, s68, 6
	s_lshl_b64 s[78:79], s[68:69], 1
	s_add_u32 s78, s80, s78
	s_addc_u32 s79, s73, s79
	s_and_b64 s[74:75], s[74:75], exec
	s_cselect_b32 s68, 12, 9
	global_load_dwordx4 v[116:119], v221, s[76:77]
	v_lshl_add_u32 v222, v146, s68, v128
	global_load_dwordx4 v[124:127], v222, s[78:79]
.Lg4b_nogl:
	s_waitcnt lgkmcnt(10)
	v_mfma_f32_32x32x16_bf16 v[48:63], v[164:167], v[104:107], v[48:63]
	ds_read_b64 v[164:165], v210 offset:1088
	ds_read_b64 v[166:167], v210 offset:1104
	v_exp_f32_e32 v68, v68
	v_pk_add_f32 v[212:213], v[66:67], v[82:83]
	v_pk_add_f32 v[214:215], v[214:215], v[212:213]
	v_exp_f32_e32 v84, v84
	v_mfma_f32_32x32x16_bf16 v[192:207], v[168:171], v[104:107], v[192:207]
	ds_read_b64 v[168:169], v211 offset:1600
	ds_read_b64 v[170:171], v211 offset:1616
	v_exp_f32_e32 v69, v69
	v_exp_f32_e32 v85, v85
	v_exp_f32_e32 v70, v70
	v_pk_add_f32 v[212:213], v[68:69], v[84:85]
	s_waitcnt lgkmcnt(12)
	v_mfma_f32_32x32x16_bf16 v[48:63], v[172:175], v[100:103], v[48:63]
	ds_read_b64 v[172:173], v210 offset:1056
	ds_read_b64 v[174:175], v210 offset:1072
	v_pk_add_f32 v[214:215], v[214:215], v[212:213]
	v_exp_f32_e32 v86, v86
	v_exp_f32_e32 v71, v71
	v_exp_f32_e32 v87, v87
	v_mfma_f32_32x32x16_bf16 v[192:207], v[176:179], v[100:103], v[192:207]
	ds_read_b64 v[176:177], v211 offset:1568
	ds_read_b64 v[178:179], v211 offset:1584
	v_cvt_pk_bf16_f32 v134, v64, v65
	v_pk_add_f32 v[212:213], v[70:71], v[86:87]
	v_pk_add_f32 v[214:215], v[214:215], v[212:213]
	v_cvt_pk_bf16_f32 v135, v66, v67
	v_cvt_pk_bf16_f32 v136, v68, v69
	v_cvt_pk_bf16_f32 v137, v70, v71
	s_waitcnt lgkmcnt(14)
	v_mfma_f32_32x32x16_bf16 v[48:63], v[184:187], v[96:99], v[48:63]
	ds_read_b64 v[184:185], v210 offset:1120
	ds_read_b64 v[186:187], v210 offset:1136
	v_cvt_pk_bf16_f32 v120, v80, v81
	v_cvt_pk_bf16_f32 v121, v82, v83
	v_cvt_pk_bf16_f32 v122, v84, v85
	v_cvt_pk_bf16_f32 v123, v86, v87
	v_mfma_f32_32x32x16_bf16 v[192:207], v[188:191], v[96:99], v[192:207]
	ds_read_b64 v[188:189], v211 offset:1632
	ds_read_b64 v[190:191], v211 offset:1648
	s_waitcnt lgkmcnt(14)
	v_mfma_f32_32x32x16_bf16 v[16:31], v[156:159], v[134:137], v[16:31]
	v_exp_f32_e32 v72, v72
	v_exp_f32_e32 v88, v88
	v_exp_f32_e32 v73, v73
	v_exp_f32_e32 v89, v89
	v_exp_f32_e32 v74, v74
	v_pk_add_f32 v[212:213], v[72:73], v[88:89]
	v_mfma_f32_32x32x16_bf16 v[0:15], v[160:163], v[134:137], v[0:15]
	v_pk_add_f32 v[214:215], v[214:215], v[212:213]
	v_exp_f32_e32 v90, v90
	v_exp_f32_e32 v75, v75
	v_exp_f32_e32 v91, v91
	v_exp_f32_e32 v76, v76
	v_pk_add_f32 v[212:213], v[74:75], v[90:91]
	s_waitcnt lgkmcnt(8)
	v_mfma_f32_32x32x16_bf16 v[16:31], v[164:167], v[120:123], v[16:31]
	v_pk_add_f32 v[214:215], v[214:215], v[212:213]
	v_exp_f32_e32 v92, v92
	v_exp_f32_e32 v77, v77
	v_exp_f32_e32 v93, v93
	v_exp_f32_e32 v78, v78
	v_mfma_f32_32x32x16_bf16 v[0:15], v[168:171], v[120:123], v[0:15]
	v_pk_add_f32 v[212:213], v[76:77], v[92:93]
	v_pk_add_f32 v[214:215], v[214:215], v[212:213]
	v_exp_f32_e32 v94, v94
	v_exp_f32_e32 v79, v79
	v_exp_f32_e32 v95, v95
	v_cvt_pk_bf16_f32 v130, v72, v73
	v_pk_add_f32 v[212:213], v[78:79], v[94:95]
	v_pk_add_f32 v[214:215], v[214:215], v[212:213]
	v_cvt_pk_bf16_f32 v131, v74, v75
	v_cvt_pk_bf16_f32 v132, v76, v77
	v_cvt_pk_bf16_f32 v133, v78, v79
	s_waitcnt lgkmcnt(4)
	s_nop 0
	v_mfma_f32_32x32x16_bf16 v[16:31], v[172:175], v[130:133], v[16:31]
	v_cvt_pk_bf16_f32 v112, v88, v89
	v_cvt_pk_bf16_f32 v113, v90, v91
	v_cvt_pk_bf16_f32 v114, v92, v93
	v_cvt_pk_bf16_f32 v115, v94, v95
	v_add_f32_e32 v212, v214, v215
	v_add_f32_e32 v148, v148, v212
	v_mfma_f32_32x32x16_bf16 v[0:15], v[176:179], v[130:133], v[0:15]
	v_max3_f32 v212, v48, v192, v52
	v_max3_f32 v213, v49, v193, v53
	v_max3_f32 v214, v50, v194, v54
	v_max3_f32 v215, v51, v195, v55
	v_max3_f32 v212, v212, v196, v56
	v_max3_f32 v213, v213, v197, v57
	v_max3_f32 v214, v214, v198, v58
	v_max3_f32 v215, v215, v199, v59
	s_waitcnt lgkmcnt(0)
	v_mfma_f32_32x32x16_bf16 v[16:31], v[184:187], v[112:115], v[16:31]
	v_max3_f32 v212, v212, v200, v60
	v_max3_f32 v213, v213, v201, v61
	v_max3_f32 v214, v214, v202, v62
	v_max3_f32 v215, v215, v203, v63
	v_max_f32_e32 v212, v212, v204
	v_max_f32_e32 v213, v213, v205
	v_max_f32_e32 v214, v214, v206
	v_max_f32_e32 v215, v215, v207
	v_mfma_f32_32x32x16_bf16 v[0:15], v[188:191], v[112:115], v[0:15]
	v_max3_f32 v212, v212, v213, v214
	v_max_f32_e32 v212, v212, v215
	v_cmp_lt_f32_e32 vcc, 0x41000000, v212
	s_cbranch_vccz .Lg4b_join
	v_mov_b32_e32 v216, v212
	v_mov_b32_e32 v217, v212
	s_nop 1
	v_permlane32_swap_b32_e32 v216, v217
	v_max_f32_e32 v212, v216, v217
	v_max_f32_e32 v222, 0, v212
	v_add_f32_e32 v149, v149, v222
	v_exp_f32_e64 v216, -v222
	v_xor_b32_e32 v32, 0x80000000, v149
	v_pk_add_f32 v[48:49], v[48:49], v[222:223] op_sel_hi:[1,0] neg_lo:[0,1] neg_hi:[0,1]
	v_pk_add_f32 v[50:51], v[50:51], v[222:223] op_sel_hi:[1,0] neg_lo:[0,1] neg_hi:[0,1]
	v_pk_add_f32 v[52:53], v[52:53], v[222:223] op_sel_hi:[1,0] neg_lo:[0,1] neg_hi:[0,1]
	v_pk_add_f32 v[54:55], v[54:55], v[222:223] op_sel_hi:[1,0] neg_lo:[0,1] neg_hi:[0,1]
	v_pk_add_f32 v[56:57], v[56:57], v[222:223] op_sel_hi:[1,0] neg_lo:[0,1] neg_hi:[0,1]
	v_pk_add_f32 v[58:59], v[58:59], v[222:223] op_sel_hi:[1,0] neg_lo:[0,1] neg_hi:[0,1]
	v_pk_add_f32 v[60:61], v[60:61], v[222:223] op_sel_hi:[1,0] neg_lo:[0,1] neg_hi:[0,1]
	v_pk_add_f32 v[62:63], v[62:63], v[222:223] op_sel_hi:[1,0] neg_lo:[0,1] neg_hi:[0,1]
	v_pk_add_f32 v[192:193], v[192:193], v[222:223] op_sel_hi:[1,0] neg_lo:[0,1] neg_hi:[0,1]
	v_pk_add_f32 v[194:195], v[194:195], v[222:223] op_sel_hi:[1,0] neg_lo:[0,1] neg_hi:[0,1]
	v_pk_add_f32 v[196:197], v[196:197], v[222:223] op_sel_hi:[1,0] neg_lo:[0,1] neg_hi:[0,1]
	v_pk_add_f32 v[198:199], v[198:199], v[222:223] op_sel_hi:[1,0] neg_lo:[0,1] neg_hi:[0,1]
	v_pk_add_f32 v[200:201], v[200:201], v[222:223] op_sel_hi:[1,0] neg_lo:[0,1] neg_hi:[0,1]
	v_pk_add_f32 v[202:203], v[202:203], v[222:223] op_sel_hi:[1,0] neg_lo:[0,1] neg_hi:[0,1]
	v_pk_add_f32 v[204:205], v[204:205], v[222:223] op_sel_hi:[1,0] neg_lo:[0,1] neg_hi:[0,1]
	v_pk_add_f32 v[206:207], v[206:207], v[222:223] op_sel_hi:[1,0] neg_lo:[0,1] neg_hi:[0,1]
	v_mov_b32_e32 v33, v32
	v_mov_b32_e32 v34, v32
	v_mov_b32_e32 v35, v32
	v_mov_b32_e32 v36, v32
	v_mov_b32_e32 v37, v32
	v_mov_b32_e32 v38, v32
	v_mov_b32_e32 v39, v32
	v_mov_b32_e32 v40, v32
	v_mov_b32_e32 v41, v32
	v_mov_b32_e32 v42, v32
	v_mov_b32_e32 v43, v32
	v_mov_b32_e32 v44, v32
	v_mov_b32_e32 v45, v32
	v_mov_b32_e32 v46, v32
	v_mov_b32_e32 v47, v32
	v_mul_f32_e32 v148, v148, v216
	v_pk_mul_f32 v[16:17], v[16:17], v[216:217] op_sel_hi:[1,0]
	v_pk_mul_f32 v[18:19], v[18:19], v[216:217] op_sel_hi:[1,0]
	v_pk_mul_f32 v[20:21], v[20:21], v[216:217] op_sel_hi:[1,0]
	v_pk_mul_f32 v[22:23], v[22:23], v[216:217] op_sel_hi:[1,0]
	v_pk_mul_f32 v[24:25], v[24:25], v[216:217] op_sel_hi:[1,0]
	v_pk_mul_f32 v[26:27], v[26:27], v[216:217] op_sel_hi:[1,0]
	v_pk_mul_f32 v[28:29], v[28:29], v[216:217] op_sel_hi:[1,0]
	v_pk_mul_f32 v[30:31], v[30:31], v[216:217] op_sel_hi:[1,0]
	v_pk_mul_f32 v[0:1], v[0:1], v[216:217] op_sel_hi:[1,0]
	v_pk_mul_f32 v[2:3], v[2:3], v[216:217] op_sel_hi:[1,0]
	v_pk_mul_f32 v[4:5], v[4:5], v[216:217] op_sel_hi:[1,0]
	v_pk_mul_f32 v[6:7], v[6:7], v[216:217] op_sel_hi:[1,0]
	v_pk_mul_f32 v[8:9], v[8:9], v[216:217] op_sel_hi:[1,0]
	v_pk_mul_f32 v[10:11], v[10:11], v[216:217] op_sel_hi:[1,0]
	v_pk_mul_f32 v[12:13], v[12:13], v[216:217] op_sel_hi:[1,0]
	v_pk_mul_f32 v[14:15], v[14:15], v[216:217] op_sel_hi:[1,0]
.Lg4b_join:
	s_add_i32 s25, s25, 1
	s_cmp_lg_u32 s25, 37
	s_barrier
	s_cbranch_scc0 .Lg4_exit
	s_mov_b32 s84, s66
	s_mov_b32 s66, s71
	s_mul_i32 s70, s84, 0x9000
	v_add_u32_e32 v208, s70, v154
	s_mov_b32 s71, s65
	s_mul_i32 s68, s71, 0x9000
	s_mov_b32 s65, s84
	v_add_u32_e32 v209, s68, v155
	v_add_u32_e32 v210, 0x4000, v209
	v_add_u32_e32 v211, 0x5000, v209
	ds_read_b128 v[156:159], v208
	ds_read_b128 v[160:163], v208 offset:4608
	ds_read_b128 v[164:167], v208 offset:32
	ds_read_b128 v[168:171], v208 offset:4640
	ds_read_b128 v[172:175], v208 offset:64
	ds_read_b128 v[176:179], v208 offset:4672
	ds_read_b128 v[184:187], v208 offset:96
	ds_read_b128 v[188:191], v208 offset:4704
	s_mul_i32 s72, s66, 0x9000
	s_add_i32 s73, s72, 0
	v_add3_u32 v218, s73, v150, v151
	v_add3_u32 v219, s73, v152, v153
	v_exp_f32_e32 v48, v48
	v_exp_f32_e32 v192, v192
	v_exp_f32_e32 v49, v49
	v_exp_f32_e32 v193, v193
	v_exp_f32_e32 v50, v50
	s_waitcnt lgkmcnt(6)
	v_mfma_f32_32x32x16_bf16 v[64:79], v[156:159], v[108:111], v[32:47]
	ds_read_b64 v[156:157], v210 offset:1024
	ds_read_b64 v[158:159], v210 offset:1040
	v_pk_add_f32 v[214:215], v[48:49], v[192:193]
	v_exp_f32_e32 v194, v194
	v_exp_f32_e32 v51, v51
	v_exp_f32_e32 v195, v195
	v_mfma_f32_32x32x16_bf16 v[80:95], v[160:163], v[108:111], v[32:47]
	ds_read_b64 v[160:161], v211 offset:1536
	ds_read_b64 v[162:163], v211 offset:1552
	s_waitcnt vmcnt(0)
	ds_write_b128 v218, v[116:119]
	ds_write_b128 v219, v[124:127] offset:17408
	s_add_i32 s68, s25, -2
	s_cmp_gt_u32 s68, 33
	s_cbranch_scc1 .Lg4a_nogl
	s_cmp_lt_u32 s68, 30
	s_cselect_b64 s[74:75], -1, 0
	s_and_b64 s[76:77], s[74:75], exec
	s_cselect_b32 s68, 0, 0xffffffe0
	s_add_i32 s68, s68, s25
	s_and_b64 s[76:77], s[74:75], exec
	s_cselect_b32 s73, s21, s27
	s_cselect_b32 s78, s20, s26
	s_lshl_b64 s[76:77], s[68:69], 14
	s_add_u32 s76, s78, s76
	s_addc_u32 s77, s73, s77
	s_and_b64 s[78:79], s[74:75], exec
	s_cselect_b32 s73, s23, s64
	s_cselect_b32 s80, s22, s63
	s_lshl_b32 s68, s68, 6
	s_lshl_b64 s[78:79], s[68:69], 1
	s_add_u32 s78, s80, s78
	s_addc_u32 s79, s73, s79
	s_and_b64 s[74:75], s[74:75], exec
	s_cselect_b32 s68, 12, 9
	global_load_dwordx4 v[116:119], v221, s[76:77]
	v_lshl_add_u32 v222, v146, s68, v128
	global_load_dwordx4 v[124:127], v222, s[78:79]
.Lg4a_nogl:
	s_waitcnt lgkmcnt(10)
	v_mfma_f32_32x32x16_bf16 v[64:79], v[164:167], v[104:107], v[64:79]
	ds_read_b64 v[164:165], v210 offset:1088
	ds_read_b64 v[166:167], v210 offset:1104
	v_exp_f32_e32 v52, v52
	v_pk_add_f32 v[212:213], v[50:51], v[194:195]
	v_pk_add_f32 v[214:215], v[214:215], v[212:213]
	v_exp_f32_e32 v196, v196
	v_mfma_f32_32x32x16_bf16 v[80:95], v[168:171], v[104:107], v[80:95]
	ds_read_b64 v[168:169], v211 offset:1600
	ds_read_b64 v[170:171], v211 offset:1616
	v_exp_f32_e32 v53, v53
	v_exp_f32_e32 v197, v197
	v_exp_f32_e32 v54, v54
	v_pk_add_f32 v[212:213], v[52:53], v[196:197]
	s_waitcnt lgkmcnt(12)
	v_mfma_f32_32x32x16_bf16 v[64:79], v[172:175], v[100:103], v[64:79]
	ds_read_b64 v[172:173], v210 offset:1056
	ds_read_b64 v[174:175], v210 offset:1072
	v_pk_add_f32 v[214:215], v[214:215], v[212:213]
	v_exp_f32_e32 v198, v198
	v_exp_f32_e32 v55, v55
	v_exp_f32_e32 v199, v199
	v_mfma_f32_32x32x16_bf16 v[80:95], v[176:179], v[100:103], v[80:95]
	ds_read_b64 v[176:177], v211 offset:1568
	ds_read_b64 v[178:179], v211 offset:1584
	v_cvt_pk_bf16_f32 v134, v48, v49
	v_pk_add_f32 v[212:213], v[54:55], v[198:199]
	v_pk_add_f32 v[214:215], v[214:215], v[212:213]
	v_cvt_pk_bf16_f32 v135, v50, v51
	v_cvt_pk_bf16_f32 v136, v52, v53
	v_cvt_pk_bf16_f32 v137, v54, v55
	s_waitcnt lgkmcnt(14)
	v_mfma_f32_32x32x16_bf16 v[64:79], v[184:187], v[96:99], v[64:79]
	ds_read_b64 v[184:185], v210 offset:1120
	ds_read_b64 v[186:187], v210 offset:1136
	v_cvt_pk_bf16_f32 v120, v192, v193
	v_cvt_pk_bf16_f32 v121, v194, v195
	v_cvt_pk_bf16_f32 v122, v196, v197
	v_cvt_pk_bf16_f32 v123, v198, v199
	v_mfma_f32_32x32x16_bf16 v[80:95], v[188:191], v[96:99], v[80:95]
	ds_read_b64 v[188:189], v211 offset:1632
	ds_read_b64 v[190:191], v211 offset:1648
	s_waitcnt lgkmcnt(14)
	v_mfma_f32_32x32x16_bf16 v[16:31], v[156:159], v[134:137], v[16:31]
	v_exp_f32_e32 v56, v56
	v_exp_f32_e32 v200, v200
	v_exp_f32_e32 v57, v57
	v_exp_f32_e32 v201, v201
	v_exp_f32_e32 v58, v58
	v_pk_add_f32 v[212:213], v[56:57], v[200:201]
	v_mfma_f32_32x32x16_bf16 v[0:15], v[160:163], v[134:137], v[0:15]
	v_pk_add_f32 v[214:215], v[214:215], v[212:213]
	v_exp_f32_e32 v202, v202
	v_exp_f32_e32 v59, v59
	v_exp_f32_e32 v203, v203
	v_exp_f32_e32 v60, v60
	v_pk_add_f32 v[212:213], v[58:59], v[202:203]
	s_waitcnt lgkmcnt(8)
	v_mfma_f32_32x32x16_bf16 v[16:31], v[164:167], v[120:123], v[16:31]
	v_pk_add_f32 v[214:215], v[214:215], v[212:213]
	v_exp_f32_e32 v204, v204
	v_exp_f32_e32 v61, v61
	v_exp_f32_e32 v205, v205
	v_exp_f32_e32 v62, v62
	v_mfma_f32_32x32x16_bf16 v[0:15], v[168:171], v[120:123], v[0:15]
	v_pk_add_f32 v[212:213], v[60:61], v[204:205]
	v_pk_add_f32 v[214:215], v[214:215], v[212:213]
	v_exp_f32_e32 v206, v206
	v_exp_f32_e32 v63, v63
	v_exp_f32_e32 v207, v207
	v_cvt_pk_bf16_f32 v130, v56, v57
	v_pk_add_f32 v[212:213], v[62:63], v[206:207]
	v_pk_add_f32 v[214:215], v[214:215], v[212:213]
	v_cvt_pk_bf16_f32 v131, v58, v59
	v_cvt_pk_bf16_f32 v132, v60, v61
	v_cvt_pk_bf16_f32 v133, v62, v63
	s_waitcnt lgkmcnt(4)
	s_nop 0
	v_mfma_f32_32x32x16_bf16 v[16:31], v[172:175], v[130:133], v[16:31]
	v_cvt_pk_bf16_f32 v112, v200, v201
	v_cvt_pk_bf16_f32 v113, v202, v203
	v_cvt_pk_bf16_f32 v114, v204, v205
	v_cvt_pk_bf16_f32 v115, v206, v207
	v_add_f32_e32 v212, v214, v215
	v_add_f32_e32 v148, v148, v212
	v_mfma_f32_32x32x16_bf16 v[0:15], v[176:179], v[130:133], v[0:15]
	v_max3_f32 v212, v64, v80, v68
	v_max3_f32 v213, v65, v81, v69
	v_max3_f32 v214, v66, v82, v70
	v_max3_f32 v215, v67, v83, v71
	v_max3_f32 v212, v212, v84, v72
	v_max3_f32 v213, v213, v85, v73
	v_max3_f32 v214, v214, v86, v74
	v_max3_f32 v215, v215, v87, v75
	s_waitcnt lgkmcnt(0)
	v_mfma_f32_32x32x16_bf16 v[16:31], v[184:187], v[112:115], v[16:31]
	v_max3_f32 v212, v212, v88, v76
	v_max3_f32 v213, v213, v89, v77
	v_max3_f32 v214, v214, v90, v78
	v_max3_f32 v215, v215, v91, v79
	v_max_f32_e32 v212, v212, v92
	v_max_f32_e32 v213, v213, v93
	v_max_f32_e32 v214, v214, v94
	v_max_f32_e32 v215, v215, v95
	v_mfma_f32_32x32x16_bf16 v[0:15], v[188:191], v[112:115], v[0:15]
	v_max3_f32 v212, v212, v213, v214
	v_max_f32_e32 v212, v212, v215
	v_cmp_lt_f32_e32 vcc, 0x41000000, v212
	s_cbranch_vccz .Lg4a_join
	v_mov_b32_e32 v216, v212
	v_mov_b32_e32 v217, v212
	s_nop 1
	v_permlane32_swap_b32_e32 v216, v217
	v_max_f32_e32 v212, v216, v217
	v_max_f32_e32 v222, 0, v212
	v_add_f32_e32 v149, v149, v222
	v_exp_f32_e64 v216, -v222
	v_xor_b32_e32 v32, 0x80000000, v149
	v_pk_add_f32 v[64:65], v[64:65], v[222:223] op_sel_hi:[1,0] neg_lo:[0,1] neg_hi:[0,1]
	v_pk_add_f32 v[66:67], v[66:67], v[222:223] op_sel_hi:[1,0] neg_lo:[0,1] neg_hi:[0,1]
	v_pk_add_f32 v[68:69], v[68:69], v[222:223] op_sel_hi:[1,0] neg_lo:[0,1] neg_hi:[0,1]
	v_pk_add_f32 v[70:71], v[70:71], v[222:223] op_sel_hi:[1,0] neg_lo:[0,1] neg_hi:[0,1]
	v_pk_add_f32 v[72:73], v[72:73], v[222:223] op_sel_hi:[1,0] neg_lo:[0,1] neg_hi:[0,1]
	v_pk_add_f32 v[74:75], v[74:75], v[222:223] op_sel_hi:[1,0] neg_lo:[0,1] neg_hi:[0,1]
	v_pk_add_f32 v[76:77], v[76:77], v[222:223] op_sel_hi:[1,0] neg_lo:[0,1] neg_hi:[0,1]
	v_pk_add_f32 v[78:79], v[78:79], v[222:223] op_sel_hi:[1,0] neg_lo:[0,1] neg_hi:[0,1]
	v_pk_add_f32 v[80:81], v[80:81], v[222:223] op_sel_hi:[1,0] neg_lo:[0,1] neg_hi:[0,1]
	v_pk_add_f32 v[82:83], v[82:83], v[222:223] op_sel_hi:[1,0] neg_lo:[0,1] neg_hi:[0,1]
	v_pk_add_f32 v[84:85], v[84:85], v[222:223] op_sel_hi:[1,0] neg_lo:[0,1] neg_hi:[0,1]
	v_pk_add_f32 v[86:87], v[86:87], v[222:223] op_sel_hi:[1,0] neg_lo:[0,1] neg_hi:[0,1]
	v_pk_add_f32 v[88:89], v[88:89], v[222:223] op_sel_hi:[1,0] neg_lo:[0,1] neg_hi:[0,1]
	v_pk_add_f32 v[90:91], v[90:91], v[222:223] op_sel_hi:[1,0] neg_lo:[0,1] neg_hi:[0,1]
	v_pk_add_f32 v[92:93], v[92:93], v[222:223] op_sel_hi:[1,0] neg_lo:[0,1] neg_hi:[0,1]
	v_pk_add_f32 v[94:95], v[94:95], v[222:223] op_sel_hi:[1,0] neg_lo:[0,1] neg_hi:[0,1]
	v_mov_b32_e32 v33, v32
	v_mov_b32_e32 v34, v32
	v_mov_b32_e32 v35, v32
	v_mov_b32_e32 v36, v32
	v_mov_b32_e32 v37, v32
	v_mov_b32_e32 v38, v32
	v_mov_b32_e32 v39, v32
	v_mov_b32_e32 v40, v32
	v_mov_b32_e32 v41, v32
	v_mov_b32_e32 v42, v32
	v_mov_b32_e32 v43, v32
	v_mov_b32_e32 v44, v32
	v_mov_b32_e32 v45, v32
	v_mov_b32_e32 v46, v32
	v_mov_b32_e32 v47, v32
	v_mul_f32_e32 v148, v148, v216
	v_pk_mul_f32 v[16:17], v[16:17], v[216:217] op_sel_hi:[1,0]
	v_pk_mul_f32 v[18:19], v[18:19], v[216:217] op_sel_hi:[1,0]
	v_pk_mul_f32 v[20:21], v[20:21], v[216:217] op_sel_hi:[1,0]
	v_pk_mul_f32 v[22:23], v[22:23], v[216:217] op_sel_hi:[1,0]
	v_pk_mul_f32 v[24:25], v[24:25], v[216:217] op_sel_hi:[1,0]
	v_pk_mul_f32 v[26:27], v[26:27], v[216:217] op_sel_hi:[1,0]
	v_pk_mul_f32 v[28:29], v[28:29], v[216:217] op_sel_hi:[1,0]
	v_pk_mul_f32 v[30:31], v[30:31], v[216:217] op_sel_hi:[1,0]
	v_pk_mul_f32 v[0:1], v[0:1], v[216:217] op_sel_hi:[1,0]
	v_pk_mul_f32 v[2:3], v[2:3], v[216:217] op_sel_hi:[1,0]
	v_pk_mul_f32 v[4:5], v[4:5], v[216:217] op_sel_hi:[1,0]
	v_pk_mul_f32 v[6:7], v[6:7], v[216:217] op_sel_hi:[1,0]
	v_pk_mul_f32 v[8:9], v[8:9], v[216:217] op_sel_hi:[1,0]
	v_pk_mul_f32 v[10:11], v[10:11], v[216:217] op_sel_hi:[1,0]
	v_pk_mul_f32 v[12:13], v[12:13], v[216:217] op_sel_hi:[1,0]
	v_pk_mul_f32 v[14:15], v[14:15], v[216:217] op_sel_hi:[1,0]
